# v24 + s_setprio 1 restored around the QK MFMA clusters of the MLA and FoX tile loops (compiler had left them at priority 0)
# speedup vs baseline: 1.0089x; 1.0089x over previous
; #define MFMA(a, b, c) __builtin_amdgcn_mfma_f32_32x32x16_bf16((a), (b), (c), 0, 0, 0)
; template <int DK, int MODE> ...
;     ...
;     if (active) {
;       f32x16 s0, s1;
;       const bf16_t* kb = sK + cur * 64 * LDK + l32 * LDK + h * 8;
;       bf16x8 kf0[NKS], kf1[NKS];
; #pragma unroll
;       for (int ks = 0; ks < NKS; ++ks) { kf0[ks] = *(const bf16x8*)(kb + ks * 16); kf1[ks] = *(const bf16x8*)(kb + 32 * LDK + ks * 16); }
;       if (MODE == 1) {
;         const float* fb = sF + cur * 64 + 4 * h;
; #pragma unroll
;         for (int g = 0; g < 4; ++g) {
;           const f32x4 f0 = *(const f32x4*)(fb + 8 * g), f1 = *(const f32x4*)(fb + 32 + 8 * g);
;           s0[4 * g] = f0.x; s0[4 * g + 1] = f0.y; s0[4 * g + 2] = f0.z; s0[4 * g + 3] = f0.w;
;           s1[4 * g] = f1.x; s1[4 * g + 1] = f1.y; s1[4 * g + 2] = f1.z; s1[4 * g + 3] = f1.w;
;         }
;       } else {
; #pragma unroll
;         for (int e = 0; e < 16; ++e) { s0[e] = 0.f; s1[e] = 0.f; }
;       }
;       __builtin_amdgcn_iglp_opt(0);
;       __builtin_amdgcn_s_setprio(1);
; #pragma unroll
;       for (int ks = 0; ks < NKS; ++ks) { s0 = MFMA(kf0[ks], qf[ks], s0); s1 = MFMA(kf1[ks], qf[ks], s1); }
;       __builtin_amdgcn_s_setprio(0);
;       const bf16_t* vb = sV + cur * 64 * 72 + l32 * 72 + h * 8;
;       bf16x8 vf0[4], vf1[4];
; #pragma unroll
;       for (int j = 0; j < 4; ++j) { vf0[j] = *(const bf16x8*)(vb + j * 16); vf1[j] = *(const bf16x8*)(vb + 32 * 72 + j * 16); }
;       __builtin_amdgcn_sched_barrier(0);
;       const bool need_mask = CAUSAL && (key0 + 63 >= tq0);
;       bf16x8 pf[4];
;       if (MODE != 2) {
;         if (need_mask) {
; #pragma unroll
;           for (int e = 0; e < 16; ++e) {
;             const int key = key0 + 8 * (e >> 2) + 4 * h + (e & 3);
;             if (key > qpos) s0[e] = -1e30f;
;             if (key + 32 > qpos) s1[e] = -1e30f;
;           }
.LBB0_526:
	s_and_b32 s11, s10, 1
	s_cmp_gt_i32 s9, s8
	s_cbranch_scc1 .Lmla_inactive
	s_mul_i32 s12, s11, 0x3400
	v_add_u32_e32 v0, s12, v175
	ds_read_b128 v[48:51], v0 offset:6656
	ds_read_b128 v[52:55], v0
	ds_read_b128 v[92:95], v0 offset:32
	ds_read_b128 v[96:99], v0 offset:6688
	ds_read_b128 v[100:103], v0 offset:64
	ds_read_b128 v[104:107], v0 offset:6720
	ds_read_b128 v[108:111], v0 offset:96
	ds_read_b128 v[132:135], v0 offset:6752
	ds_read_b128 v[136:139], v0 offset:128
	ds_read_b128 v[140:143], v0 offset:6784
	ds_read_b128 v[176:179], v0 offset:160
	ds_read_b128 v[180:183], v0 offset:6816
	s_setprio 1
	s_waitcnt lgkmcnt(10)
	v_mfma_f32_32x32x16_bf16 v[64:79], v[52:55], v[80:83], 0
	s_mul_i32 s12, s11, 0x2400
	v_add_u32_e32 v0, s12, v157
	v_mfma_f32_32x32x16_bf16 v[48:63], v[48:51], v[80:83], 0
	v_lshl_add_u64 v[2:3], v[170:171], 0, s[46:47]
	global_load_dwordx4 v[88:91], v[2:3], off
	s_waitcnt lgkmcnt(9)
	v_mfma_f32_32x32x16_bf16 v[64:79], v[92:95], v[128:131], v[64:79]
	ds_read_b128 v[92:95], v0 offset:31328
	s_waitcnt lgkmcnt(9)
	v_mfma_f32_32x32x16_bf16 v[48:63], v[96:99], v[128:131], v[48:63]
	v_lshl_add_u64 v[2:3], v[168:169], 0, s[46:47]
	global_load_dwordx4 v[84:87], v[2:3], off
	ds_read_b128 v[96:99], v0 offset:26720
	s_waitcnt lgkmcnt(9)
	v_mfma_f32_32x32x16_bf16 v[64:79], v[100:103], v[124:127], v[64:79]
	ds_read_b128 v[100:103], v0 offset:26688
	s_waitcnt lgkmcnt(9)
	v_mfma_f32_32x32x16_bf16 v[48:63], v[104:107], v[124:127], v[48:63]
	v_lshl_add_u64 v[2:3], v[166:167], 0, s[46:47]
	global_load_dwordx4 v[10:13], v[2:3], off
	ds_read_b128 v[104:107], v0 offset:31296
	s_waitcnt lgkmcnt(9)
	v_mfma_f32_32x32x16_bf16 v[64:79], v[108:111], v[120:123], v[64:79]
	ds_read_b128 v[108:111], v0 offset:26656
	s_waitcnt lgkmcnt(9)
	v_mfma_f32_32x32x16_bf16 v[48:63], v[132:135], v[120:123], v[48:63]
	global_load_dwordx4 v[6:9], v[164:165], off
	ds_read_b128 v[132:135], v0 offset:31264
	s_waitcnt lgkmcnt(9)
	v_mfma_f32_32x32x16_bf16 v[64:79], v[136:139], v[116:119], v[64:79]
	ds_read_b128 v[136:139], v0 offset:26624
	s_waitcnt lgkmcnt(9)
	v_mfma_f32_32x32x16_bf16 v[48:63], v[140:143], v[116:119], v[48:63]
	s_nop 0
	global_load_dwordx4 v[2:5], v[162:163], off
	ds_read_b128 v[140:143], v0 offset:31232
	s_waitcnt lgkmcnt(9)
	v_mfma_f32_32x32x16_bf16 v[64:79], v[176:179], v[112:115], v[64:79]
	s_waitcnt lgkmcnt(8)
	v_mfma_f32_32x32x16_bf16 v[48:63], v[180:183], v[112:115], v[48:63]
	s_setprio 0
	s_add_i32 s12, s9, 63
	s_cmp_lt_i32 s12, s1
	s_cbranch_scc1 .LBB0_529
	v_add_u32_e32 v0, s9, v149
	v_add_u32_e32 v14, 32, v0
	v_cmp_le_i32_e32 vcc, v14, v152
	v_add_u32_e32 v14, 33, v0
	s_nop 4
	v_cndmask_b32_e32 v48, v198, v48, vcc
	v_cmp_lt_i32_e32 vcc, v0, v152
	s_nop 1
	v_cndmask_b32_e32 v65, v198, v65, vcc
	v_cmp_le_i32_e32 vcc, v0, v152
	s_nop 1
	v_cndmask_b32_e32 v64, v198, v64, vcc
	v_cmp_le_i32_e32 vcc, v14, v152
	v_add_u32_e32 v14, 2, v0
	s_nop 0
	v_cndmask_b32_e32 v49, v198, v49, vcc
	v_cmp_le_i32_e32 vcc, v14, v152
	v_add_u32_e32 v14, 34, v0
	s_nop 0
	v_cndmask_b32_e32 v66, v198, v66, vcc
	v_cmp_le_i32_e32 vcc, v14, v152
	v_add_u32_e32 v14, 3, v0
	s_nop 0
	v_cndmask_b32_e32 v50, v198, v50, vcc
	v_cmp_le_i32_e32 vcc, v14, v152
	v_add_u32_e32 v14, 35, v0
	s_nop 0
	v_cndmask_b32_e32 v67, v198, v67, vcc
	v_cmp_le_i32_e32 vcc, v14, v152
	v_add_u32_e32 v14, 8, v0
	s_nop 0
	v_cndmask_b32_e32 v51, v198, v51, vcc
	v_cmp_le_i32_e32 vcc, v14, v152
	v_add_u32_e32 v14, 40, v0
	s_nop 0
	v_cndmask_b32_e32 v68, v198, v68, vcc
	v_cmp_le_i32_e32 vcc, v14, v152
	v_add_u32_e32 v14, 9, v0
	s_nop 0
	v_cndmask_b32_e32 v52, v198, v52, vcc
	v_cmp_le_i32_e32 vcc, v14, v152
	v_add_u32_e32 v14, 41, v0
	s_nop 0
	v_cndmask_b32_e32 v69, v198, v69, vcc
	v_cmp_le_i32_e32 vcc, v14, v152
	v_add_u32_e32 v14, 10, v0
	s_nop 0
	v_cndmask_b32_e32 v53, v198, v53, vcc
	v_cmp_le_i32_e32 vcc, v14, v152
	v_add_u32_e32 v14, 42, v0
	s_nop 0
	v_cndmask_b32_e32 v70, v198, v70, vcc
	v_cmp_le_i32_e32 vcc, v14, v152
	v_add_u32_e32 v14, 11, v0
	s_nop 0
	v_cndmask_b32_e32 v54, v198, v54, vcc
	v_cmp_le_i32_e32 vcc, v14, v152
	v_add_u32_e32 v14, 43, v0
	s_nop 0
	v_cndmask_b32_e32 v71, v198, v71, vcc
	v_cmp_le_i32_e32 vcc, v14, v152
	v_add_u32_e32 v14, 16, v0
	s_nop 0
	v_cndmask_b32_e32 v55, v198, v55, vcc
	v_cmp_le_i32_e32 vcc, v14, v152
	v_add_u32_e32 v14, 48, v0
	s_nop 0
	v_cndmask_b32_e32 v72, v198, v72, vcc
	v_cmp_le_i32_e32 vcc, v14, v152
	v_add_u32_e32 v14, 17, v0
	s_nop 0
	v_cndmask_b32_e32 v56, v198, v56, vcc
	v_cmp_le_i32_e32 vcc, v14, v152
	v_add_u32_e32 v14, 49, v0
	s_nop 0
	v_cndmask_b32_e32 v73, v198, v73, vcc
	v_cmp_le_i32_e32 vcc, v14, v152
	v_add_u32_e32 v14, 18, v0
	s_nop 0
	v_cndmask_b32_e32 v57, v198, v57, vcc
	v_cmp_le_i32_e32 vcc, v14, v152
	v_add_u32_e32 v14, 50, v0
	s_nop 0
	v_cndmask_b32_e32 v74, v198, v74, vcc
	v_cmp_le_i32_e32 vcc, v14, v152
	v_add_u32_e32 v14, 19, v0
	s_nop 0
	v_cndmask_b32_e32 v58, v198, v58, vcc
	v_cmp_le_i32_e32 vcc, v14, v152
	v_add_u32_e32 v14, 51, v0
	s_nop 0
	v_cndmask_b32_e32 v75, v198, v75, vcc
	v_cmp_le_i32_e32 vcc, v14, v152
	v_add_u32_e32 v14, 24, v0
	s_nop 0
	v_cndmask_b32_e32 v59, v198, v59, vcc
	v_cmp_le_i32_e32 vcc, v14, v152
	v_add_u32_e32 v14, 56, v0
	s_nop 0
	v_cndmask_b32_e32 v76, v198, v76, vcc
	v_cmp_le_i32_e32 vcc, v14, v152
	v_add_u32_e32 v14, 25, v0
	s_nop 0
	v_cndmask_b32_e32 v60, v198, v60, vcc
	v_cmp_le_i32_e32 vcc, v14, v152
	v_add_u32_e32 v14, 57, v0
	s_nop 0
	v_cndmask_b32_e32 v77, v198, v77, vcc
	v_cmp_le_i32_e32 vcc, v14, v152
	v_add_u32_e32 v14, 26, v0
	s_nop 0
	v_cndmask_b32_e32 v61, v198, v61, vcc
	v_cmp_le_i32_e32 vcc, v14, v152
	v_add_u32_e32 v14, 58, v0
	s_nop 0
	v_cndmask_b32_e32 v78, v198, v78, vcc
	v_cmp_le_i32_e32 vcc, v14, v152
	v_add_u32_e32 v14, 27, v0
	v_add_u32_e32 v0, 59, v0
	v_cndmask_b32_e32 v62, v198, v62, vcc
	v_cmp_le_i32_e32 vcc, v14, v152
	s_nop 1
	v_cndmask_b32_e32 v79, v198, v79, vcc
	v_cmp_le_i32_e32 vcc, v0, v152
	s_nop 1
	v_cndmask_b32_e32 v63, v198, v63, vcc

; #define MFMA(a, b, c) __builtin_amdgcn_mfma_f32_32x32x16_bf16((a), (b), (c), 0, 0, 0)
; template <int DK, int MODE> ...
;     ...
;     if (active) {
;       f32x16 s0, s1;
;       const bf16_t* kb = sK + cur * 64 * LDK + l32 * LDK + h * 8;
;       bf16x8 kf0[NKS], kf1[NKS];
; #pragma unroll
;       for (int ks = 0; ks < NKS; ++ks) { kf0[ks] = *(const bf16x8*)(kb + ks * 16); kf1[ks] = *(const bf16x8*)(kb + 32 * LDK + ks * 16); }
;       if (MODE == 1) {
;         const float* fb = sF + cur * 64 + 4 * h;
; #pragma unroll
;         for (int g = 0; g < 4; ++g) {
;           const f32x4 f0 = *(const f32x4*)(fb + 8 * g), f1 = *(const f32x4*)(fb + 32 + 8 * g);
;           s0[4 * g] = f0.x; s0[4 * g + 1] = f0.y; s0[4 * g + 2] = f0.z; s0[4 * g + 3] = f0.w;
;           s1[4 * g] = f1.x; s1[4 * g + 1] = f1.y; s1[4 * g + 2] = f1.z; s1[4 * g + 3] = f1.w;
;         }
;       } else {
; #pragma unroll
;         for (int e = 0; e < 16; ++e) { s0[e] = 0.f; s1[e] = 0.f; }
;       }
;       __builtin_amdgcn_iglp_opt(0);
;       __builtin_amdgcn_s_setprio(1);
; #pragma unroll
;       for (int ks = 0; ks < NKS; ++ks) { s0 = MFMA(kf0[ks], qf[ks], s0); s1 = MFMA(kf1[ks], qf[ks], s1); }
;       __builtin_amdgcn_s_setprio(0);
;       const bf16_t* vb = sV + cur * 64 * 72 + l32 * 72 + h * 8;
;       bf16x8 vf0[4], vf1[4];
; #pragma unroll
;       for (int j = 0; j < 4; ++j) { vf0[j] = *(const bf16x8*)(vb + j * 16); vf1[j] = *(const bf16x8*)(vb + 32 * 72 + j * 16); }
;       __builtin_amdgcn_sched_barrier(0);
;       const bool need_mask = CAUSAL && (key0 + 63 >= tq0);
;       bf16x8 pf[4];
;       if (MODE != 2) {
;         if (need_mask) {
; #pragma unroll
;           for (int e = 0; e < 16; ++e) {
;             const int key = key0 + 8 * (e >> 2) + 4 * h + (e & 3);
;             if (key > qpos) s0[e] = -1e30f;
;             if (key + 32 > qpos) s1[e] = -1e30f;
;           }
.LBB0_562:
	s_add_i32 s11, s2, -1
	s_and_b32 s11, s11, 1
	s_sub_i32 s13, s10, 64
	s_cmp_gt_i32 s13, s12
	s_cbranch_scc1 .LBB0_568
	s_mul_i32 s13, s11, 0x2400
	v_add_u32_e32 v168, s13, v137
	v_lshl_or_b32 v46, s11, 8, v132
	ds_read_b128 v[98:101], v168 offset:4608
	ds_read_b128 v[102:105], v168
	ds_read_b128 v[106:109], v168 offset:32
	ds_read_b128 v[110:113], v168 offset:4640
	ds_read_b128 v[114:117], v168 offset:64
	ds_read_b128 v[118:121], v168 offset:4672
	ds_read_b128 v[122:125], v168 offset:96
	ds_read_b128 v[50:53], v46 offset:36864
	ds_read_b128 v[54:57], v46 offset:36896
	ds_read_b128 v[34:37], v46 offset:36992
	ds_read_b128 v[38:41], v46 offset:37024
	ds_read_b128 v[58:61], v46 offset:36928
	ds_read_b128 v[42:45], v46 offset:37056
	ds_read_b128 v[62:65], v46 offset:36960
	ds_read_b128 v[46:49], v46 offset:37088
	ds_read_b128 v[164:167], v168 offset:4704
	s_setprio 1
	s_waitcnt lgkmcnt(2)
	v_mfma_f32_32x32x16_bf16 v[50:65], v[102:105], v[66:69], v[50:65]
	ds_read_b128 v[126:129], v168 offset:23040
	ds_read_b128 v[102:105], v168 offset:18528
	s_waitcnt lgkmcnt(3)
	v_mfma_f32_32x32x16_bf16 v[34:49], v[98:101], v[66:69], v[34:49]
	ds_read_b128 v[98:101], v168 offset:23136
	v_mfma_f32_32x32x16_bf16 v[50:65], v[106:109], v[70:73], v[50:65]
	ds_read_b128 v[106:109], v168 offset:18496
	v_mfma_f32_32x32x16_bf16 v[34:49], v[110:113], v[70:73], v[34:49]
	ds_read_b128 v[110:113], v168 offset:23104
	v_mfma_f32_32x32x16_bf16 v[50:65], v[114:117], v[74:77], v[50:65]
	ds_read_b128 v[114:117], v168 offset:18464
	v_mfma_f32_32x32x16_bf16 v[34:49], v[118:121], v[74:77], v[34:49]
	ds_read_b128 v[118:121], v168 offset:23072
	v_mfma_f32_32x32x16_bf16 v[50:65], v[122:125], v[78:81], v[50:65]
	ds_read_b128 v[122:125], v168 offset:18432
	s_waitcnt lgkmcnt(8)
	v_mfma_f32_32x32x16_bf16 v[34:49], v[164:167], v[78:81], v[34:49]
	s_setprio 0
	s_add_i32 s13, s10, -1
	s_cmp_lt_i32 s13, s1
	s_cbranch_scc1 .LBB0_565
	v_add_u32_e32 v164, s10, v162
	v_subrev_u32_e32 v166, 32, v164
	v_subrev_u32_e32 v165, 64, v164
	v_cmp_le_i32_e32 vcc, v166, v130
	s_nop 4
	v_cndmask_b32_e32 v34, v198, v34, vcc
	v_cmp_lt_i32_e32 vcc, v165, v130
	s_nop 1
	v_cndmask_b32_e32 v51, v198, v51, vcc
	v_cmp_le_i32_e32 vcc, v165, v130
	v_subrev_u32_e32 v165, 31, v164
	s_nop 0
	v_cndmask_b32_e32 v50, v198, v50, vcc
	v_cmp_le_i32_e32 vcc, v165, v130
	v_subrev_u32_e32 v165, 62, v164
	s_nop 0
	v_cndmask_b32_e32 v35, v198, v35, vcc
	v_cmp_le_i32_e32 vcc, v165, v130
	v_subrev_u32_e32 v165, 30, v164
	s_nop 0
	v_cndmask_b32_e32 v52, v198, v52, vcc
	v_cmp_le_i32_e32 vcc, v165, v130
	v_subrev_u32_e32 v165, 61, v164
	s_nop 0
	v_cndmask_b32_e32 v36, v198, v36, vcc
	v_cmp_le_i32_e32 vcc, v165, v130
	v_subrev_u32_e32 v165, 29, v164
	s_nop 0
	v_cndmask_b32_e32 v53, v198, v53, vcc
	v_cmp_le_i32_e32 vcc, v165, v130
	v_subrev_u32_e32 v165, 56, v164
	s_nop 0
	v_cndmask_b32_e32 v37, v198, v37, vcc
	v_cmp_le_i32_e32 vcc, v165, v130
	v_subrev_u32_e32 v165, 24, v164
	s_nop 0
	v_cndmask_b32_e32 v54, v198, v54, vcc
	v_cmp_le_i32_e32 vcc, v165, v130
	v_subrev_u32_e32 v165, 55, v164
	s_nop 0
	v_cndmask_b32_e32 v38, v198, v38, vcc
	v_cmp_le_i32_e32 vcc, v165, v130
	v_subrev_u32_e32 v165, 23, v164
	s_nop 0
	v_cndmask_b32_e32 v55, v198, v55, vcc
	v_cmp_le_i32_e32 vcc, v165, v130
	v_subrev_u32_e32 v165, 54, v164
	s_nop 0
	v_cndmask_b32_e32 v39, v198, v39, vcc
	v_cmp_le_i32_e32 vcc, v165, v130
	v_subrev_u32_e32 v165, 22, v164
	s_nop 0
	v_cndmask_b32_e32 v56, v198, v56, vcc
	v_cmp_le_i32_e32 vcc, v165, v130
	v_subrev_u32_e32 v165, 53, v164
	s_nop 0
	v_cndmask_b32_e32 v40, v198, v40, vcc
	v_cmp_le_i32_e32 vcc, v165, v130
	v_subrev_u32_e32 v165, 21, v164
	s_nop 0
	v_cndmask_b32_e32 v57, v198, v57, vcc
	v_cmp_le_i32_e32 vcc, v165, v130
	v_subrev_u32_e32 v165, 48, v164
	s_nop 0
	v_cndmask_b32_e32 v41, v198, v41, vcc
	v_cmp_le_i32_e32 vcc, v165, v130
	v_add_u32_e32 v165, -16, v164
	s_nop 0
	v_cndmask_b32_e32 v58, v198, v58, vcc
	v_cmp_le_i32_e32 vcc, v165, v130
	v_subrev_u32_e32 v165, 47, v164
	s_nop 0
	v_cndmask_b32_e32 v42, v198, v42, vcc
	v_cmp_le_i32_e32 vcc, v165, v130
	v_add_u32_e32 v165, -15, v164
	s_nop 0
	v_cndmask_b32_e32 v59, v198, v59, vcc
	v_cmp_le_i32_e32 vcc, v165, v130
	v_subrev_u32_e32 v165, 46, v164
	s_nop 0
	v_cndmask_b32_e32 v43, v198, v43, vcc
	v_cmp_le_i32_e32 vcc, v165, v130
	v_add_u32_e32 v165, -14, v164
	s_nop 0
	v_cndmask_b32_e32 v60, v198, v60, vcc
	v_cmp_le_i32_e32 vcc, v165, v130
	v_subrev_u32_e32 v165, 45, v164
	s_nop 0
	v_cndmask_b32_e32 v44, v198, v44, vcc
	v_cmp_le_i32_e32 vcc, v165, v130
	v_add_u32_e32 v165, -13, v164
	s_nop 0
	v_cndmask_b32_e32 v61, v198, v61, vcc
	v_cmp_le_i32_e32 vcc, v165, v130
	v_subrev_u32_e32 v165, 40, v164
	s_nop 0
	v_cndmask_b32_e32 v45, v198, v45, vcc
	v_cmp_le_i32_e32 vcc, v165, v130
	v_add_u32_e32 v165, -8, v164
	s_nop 0
	v_cndmask_b32_e32 v62, v198, v62, vcc
	v_cmp_le_i32_e32 vcc, v165, v130
	v_subrev_u32_e32 v165, 39, v164
	s_nop 0
	v_cndmask_b32_e32 v46, v198, v46, vcc
	v_cmp_le_i32_e32 vcc, v165, v130
	v_add_u32_e32 v165, -7, v164
	s_nop 0
	v_cndmask_b32_e32 v63, v198, v63, vcc
	v_cmp_le_i32_e32 vcc, v165, v130
	v_subrev_u32_e32 v165, 38, v164
	s_nop 0
	v_cndmask_b32_e32 v47, v198, v47, vcc
	v_cmp_le_i32_e32 vcc, v165, v130
	v_add_u32_e32 v165, -6, v164
	s_nop 0
	v_cndmask_b32_e32 v64, v198, v64, vcc
	v_cmp_le_i32_e32 vcc, v165, v130
	v_subrev_u32_e32 v165, 37, v164
	v_add_u32_e32 v164, -5, v164
	v_cndmask_b32_e32 v48, v198, v48, vcc
	v_cmp_le_i32_e32 vcc, v165, v130
	s_nop 1
	v_cndmask_b32_e32 v65, v198, v65, vcc
	v_cmp_le_i32_e32 vcc, v164, v130
	s_nop 1
	v_cndmask_b32_e32 v49, v198, v49, vcc
